# FF1 K-loop: LDS-DMA loads addressed as SGPR base + 32-bit lane offset instead of 64-bit per-lane addresses (16 v_lshl_add_u64 less per iteration)
# speedup vs baseline: 1.0063x; 1.0063x over previous
; #define PG8_STAGE(bufoff, gbase, voff) do { _Pragma("unroll") for (int _i = 0; _i < 2; ++_i) \
;         __builtin_amdgcn_global_load_lds((const unsigned*)((const char*)(gbase) + (voff)[_i]), (PG8_LAS unsigned*)(lds + (bufoff) + ldsw + _i * 8192), 16, 0, 0); } while (0)
; #define PG8_LDA(dst, b, h) do { _Pragma("unroll") for (int m = 0; m < 4; ++m) _Pragma("unroll") for (int k = 0; k < 2; ++k) dst[m][k] = *(const PG8_LAS bf16x8*)(lds + PG8_SA(b, h) + aoff + m * 2048 + k * 1024); } while (0)
; #define PG8_LDB(dst, b, h) do { _Pragma("unroll") for (int n = 0; n < 2; ++n) _Pragma("unroll") for (int k = 0; k < 2; ++k) dst[n][k] = *(const PG8_LAS bf16x8*)(lds + PG8_SB(b, h) + boff + n * 2048 + k * 1024); } while (0)
; #define PG8_MMA(ai, bj, At, Bt) do { __builtin_amdgcn_s_setprio(1); _Pragma("unroll") for (int m = 0; m < 4; ++m) _Pragma("unroll") for (int n = 0; n < 2; ++n) _Pragma("unroll") for (int k = 0; k < 2; ++k) \
;         acc[ai][bj][m][n] = __builtin_amdgcn_mfma_f32_16x16x32_bf16(Bt[n][k], At[m][k], acc[ai][bj][m][n], 0, 0, 0); __builtin_amdgcn_s_setprio(0); } while (0)
; #define PG8_WAIT_V(n) asm volatile("s_waitcnt vmcnt(" #n ")" ::: "memory")
; #define PG8_BAR __builtin_amdgcn_s_barrier()
; template <class Epi, class Sched, bool ALIGN_EPI = false, bool SP2 = false>
; __device__ __forceinline__ void gemm_phase(PG8_LAS unsigned char* lds, const Gemm g, const Sched& S, const Epi& E) {
;     ...
;         for (int t = 0; t < nt; t += 2) {
;             const bool last = (t == nt - 2);
;             const char* a1 = cA + (size_t)(t + 1) * kstep;
;             const char* a2 = last ? nA : cA + (size_t)(t + 2) * kstep; const char* b2 = last ? nB : cB + (size_t)(t + 2) * kstep;
;             const char* a3 = a2 + kstep; const char* b3 = b2 + kstep;
;             if (last && has_next) S.a_ready(nxt);
;             if constexpr (SP2) {
;             PG8_LDB(B0, 0, 0); PG8_LDB(B1, 0, 1); PG8_SCHED; PG8_LDA(At, 0, 0); PG8_STAGE(PG8_SA(1, 1), a1 + hstepA, voffA);
;             PG8_WAIT_V(8); PG8_WAIT_L(0); PG8_BAR; PG8_MMA(0, 0, At, B0); PG8_MMA(0, 1, At, B1); PG8_BAR; PG8_SCHED;
;             PG8_LDA(At, 0, 1); PG8_STAGE(PG8_SB(0, 0), b2, voffB); PG8_STAGE(PG8_SB(0, 1), b2 + hstepB, voffB); PG8_STAGE(PG8_SA(0, 0), a2, voffA);
;             PG8_WAIT_V(8); PG8_WAIT_L(0); PG8_BAR; PG8_MMA(1, 0, At, B0); PG8_MMA(1, 1, At, B1); PG8_BAR; PG8_SCHED;
.LBB0_1007:
	ds_read_b128 v[128:131], v176
	ds_read_b128 v[132:135], v176 offset:1024
	ds_read_b128 v[136:139], v176 offset:2048
	ds_read_b128 v[140:143], v176 offset:3072
	ds_read_b128 v[162:165], v177
	ds_read_b128 v[166:169], v177 offset:1024
	ds_read_b128 v[170:173], v177 offset:2048
	ds_read_b128 v[180:183], v177 offset:3072
	s_add_u32 s36, s34, 0xfffc0080
	s_addc_u32 s37, s35, -1
	s_cmp_eq_u32 s56, 12
	s_cselect_b32 s39, s25, s37
	s_cselect_b32 s38, s52, s36
	s_cselect_b32 s37, s23, s55
	s_cselect_b32 s36, s53, s54
	s_add_i32 m0, s41, 0xc000
	ds_read_b128 v[186:189], v178
	ds_read_b128 v[190:193], v178 offset:1024
	ds_read_b128 v[194:197], v178 offset:2048
	ds_read_b128 v[198:201], v178 offset:3072
	ds_read_b128 v[202:205], v178 offset:4096
	ds_read_b128 v[206:209], v178 offset:5120
	ds_read_b128 v[210:213], v178 offset:6144
	ds_read_b128 v[214:217], v178 offset:7168
	global_load_lds_dwordx4 v154, s[34:35]
	s_add_i32 m0, s41, 0xe000
	s_nop 0
	global_load_lds_dwordx4 v156, s[34:35]
	s_waitcnt vmcnt(8)
	s_waitcnt lgkmcnt(0)
	s_barrier
	s_setprio 1
	s_waitcnt lgkmcnt(0)
	v_mfma_f32_16x16x32_bf16 v[124:127], v[128:131], v[186:189], v[124:127]
	v_mfma_f32_16x16x32_bf16 v[120:123], v[136:139], v[186:189], v[120:123]
	v_mfma_f32_16x16x32_bf16 v[108:111], v[128:131], v[194:197], v[108:111]
	v_mfma_f32_16x16x32_bf16 v[104:107], v[136:139], v[194:197], v[104:107]
	v_mfma_f32_16x16x32_bf16 v[92:95], v[128:131], v[202:205], v[92:95]
	v_mfma_f32_16x16x32_bf16 v[88:91], v[136:139], v[202:205], v[88:91]
	v_mfma_f32_16x16x32_bf16 v[76:79], v[128:131], v[210:213], v[76:79]
	v_mfma_f32_16x16x32_bf16 v[72:75], v[136:139], v[210:213], v[72:75]
	v_mfma_f32_16x16x32_bf16 v[124:127], v[132:135], v[190:193], v[124:127]
	v_mfma_f32_16x16x32_bf16 v[120:123], v[140:143], v[190:193], v[120:123]
	v_mfma_f32_16x16x32_bf16 v[108:111], v[132:135], v[198:201], v[108:111]
	v_mfma_f32_16x16x32_bf16 v[104:107], v[140:143], v[198:201], v[104:107]
	v_mfma_f32_16x16x32_bf16 v[92:95], v[132:135], v[206:209], v[92:95]
	v_mfma_f32_16x16x32_bf16 v[88:91], v[140:143], v[206:209], v[88:91]
	v_mfma_f32_16x16x32_bf16 v[76:79], v[132:135], v[214:217], v[76:79]
	v_mfma_f32_16x16x32_bf16 v[72:75], v[140:143], v[214:217], v[72:75]
	v_mfma_f32_16x16x32_bf16 v[116:119], v[162:165], v[186:189], v[116:119]
	v_mfma_f32_16x16x32_bf16 v[112:115], v[170:173], v[186:189], v[112:115]
	v_mfma_f32_16x16x32_bf16 v[100:103], v[162:165], v[194:197], v[100:103]
	v_mfma_f32_16x16x32_bf16 v[96:99], v[170:173], v[194:197], v[96:99]
	v_mfma_f32_16x16x32_bf16 v[84:87], v[162:165], v[202:205], v[84:87]
	v_mfma_f32_16x16x32_bf16 v[80:83], v[170:173], v[202:205], v[80:83]
	v_mfma_f32_16x16x32_bf16 v[68:71], v[162:165], v[210:213], v[68:71]
	v_mfma_f32_16x16x32_bf16 v[64:67], v[170:173], v[210:213], v[64:67]
	v_mfma_f32_16x16x32_bf16 v[116:119], v[166:169], v[190:193], v[116:119]
	v_mfma_f32_16x16x32_bf16 v[112:115], v[180:183], v[190:193], v[112:115]
	v_mfma_f32_16x16x32_bf16 v[100:103], v[166:169], v[198:201], v[100:103]
	v_mfma_f32_16x16x32_bf16 v[96:99], v[180:183], v[198:201], v[96:99]
	v_mfma_f32_16x16x32_bf16 v[84:87], v[166:169], v[206:209], v[84:87]
	v_mfma_f32_16x16x32_bf16 v[80:83], v[180:183], v[206:209], v[80:83]
	v_mfma_f32_16x16x32_bf16 v[68:71], v[166:169], v[214:217], v[68:71]
	v_mfma_f32_16x16x32_bf16 v[64:67], v[180:183], v[214:217], v[64:67]
	s_setprio 0
	s_barrier
	s_add_i32 s57, s48, s40
	s_mov_b32 m0, s57
	ds_read_b128 v[186:189], v178 offset:16384
	ds_read_b128 v[190:193], v178 offset:17408
	ds_read_b128 v[194:197], v178 offset:18432
	ds_read_b128 v[198:201], v178 offset:19456
	ds_read_b128 v[202:205], v178 offset:20480
	ds_read_b128 v[206:209], v178 offset:21504
	ds_read_b128 v[210:213], v178 offset:22528
	ds_read_b128 v[214:217], v178 offset:23552
	global_load_lds_dwordx4 v146, s[36:37]
	s_add_i32 m0, s57, 0x2000
	s_add_u32 s58, s36, 0x40000
	s_addc_u32 s59, s37, 0
	s_add_u32 s80, s38, s12
	s_addc_u32 s81, s39, s13
	s_add_i32 s57, s49, s40
	global_load_lds_dwordx4 v150, s[36:37]
	s_mov_b32 m0, s57
	s_nop 0
	global_load_lds_dwordx4 v146, s[58:59]
	s_add_i32 m0, s57, 0x2000
	s_nop 0
	global_load_lds_dwordx4 v150, s[58:59]
	s_mov_b32 m0, s41
	s_nop 0
	global_load_lds_dwordx4 v144, s[38:39]
	s_mov_b32 m0, s42
	s_nop 0
	global_load_lds_dwordx4 v148, s[38:39]
	s_waitcnt vmcnt(8)
	s_waitcnt lgkmcnt(0)
	s_barrier
	s_setprio 1
	s_waitcnt lgkmcnt(0)
	v_mfma_f32_16x16x32_bf16 v[60:63], v[128:131], v[186:189], v[60:63]
	v_mfma_f32_16x16x32_bf16 v[56:59], v[136:139], v[186:189], v[56:59]
	v_mfma_f32_16x16x32_bf16 v[44:47], v[128:131], v[194:197], v[44:47]
	v_mfma_f32_16x16x32_bf16 v[40:43], v[136:139], v[194:197], v[40:43]
	v_mfma_f32_16x16x32_bf16 v[28:31], v[128:131], v[202:205], v[28:31]
	v_mfma_f32_16x16x32_bf16 v[24:27], v[136:139], v[202:205], v[24:27]
	v_mfma_f32_16x16x32_bf16 v[12:15], v[128:131], v[210:213], v[12:15]
	v_mfma_f32_16x16x32_bf16 v[8:11], v[136:139], v[210:213], v[8:11]
	v_mfma_f32_16x16x32_bf16 v[60:63], v[132:135], v[190:193], v[60:63]
	v_mfma_f32_16x16x32_bf16 v[56:59], v[140:143], v[190:193], v[56:59]
	v_mfma_f32_16x16x32_bf16 v[44:47], v[132:135], v[198:201], v[44:47]
	v_mfma_f32_16x16x32_bf16 v[40:43], v[140:143], v[198:201], v[40:43]
	v_mfma_f32_16x16x32_bf16 v[28:31], v[132:135], v[206:209], v[28:31]
	v_mfma_f32_16x16x32_bf16 v[24:27], v[140:143], v[206:209], v[24:27]
	v_mfma_f32_16x16x32_bf16 v[12:15], v[132:135], v[214:217], v[12:15]
	v_mfma_f32_16x16x32_bf16 v[8:11], v[140:143], v[214:217], v[8:11]
	v_mfma_f32_16x16x32_bf16 v[52:55], v[162:165], v[186:189], v[52:55]
	v_mfma_f32_16x16x32_bf16 v[48:51], v[170:173], v[186:189], v[48:51]
	v_mfma_f32_16x16x32_bf16 v[36:39], v[162:165], v[194:197], v[36:39]
	v_mfma_f32_16x16x32_bf16 v[32:35], v[170:173], v[194:197], v[32:35]
	v_mfma_f32_16x16x32_bf16 v[20:23], v[162:165], v[202:205], v[20:23]
	v_mfma_f32_16x16x32_bf16 v[16:19], v[170:173], v[202:205], v[16:19]
	v_mfma_f32_16x16x32_bf16 v[4:7], v[162:165], v[210:213], v[4:7]
	v_mfma_f32_16x16x32_bf16 v[0:3], v[170:173], v[210:213], v[0:3]
	v_mfma_f32_16x16x32_bf16 v[52:55], v[166:169], v[190:193], v[52:55]
	v_mfma_f32_16x16x32_bf16 v[48:51], v[180:183], v[190:193], v[48:51]
	v_mfma_f32_16x16x32_bf16 v[36:39], v[166:169], v[198:201], v[36:39]
	v_mfma_f32_16x16x32_bf16 v[32:35], v[180:183], v[198:201], v[32:35]
	v_mfma_f32_16x16x32_bf16 v[20:23], v[166:169], v[206:209], v[20:23]
	v_mfma_f32_16x16x32_bf16 v[16:19], v[180:183], v[206:209], v[16:19]
	v_mfma_f32_16x16x32_bf16 v[4:7], v[166:169], v[214:217], v[4:7]
	v_mfma_f32_16x16x32_bf16 v[0:3], v[180:183], v[214:217], v[0:3]
	s_setprio 0
	s_barrier
; #define PG8_STAGE(bufoff, gbase, voff) do { _Pragma("unroll") for (int _i = 0; _i < 2; ++_i) \
;         __builtin_amdgcn_global_load_lds((const unsigned*)((const char*)(gbase) + (voff)[_i]), (PG8_LAS unsigned*)(lds + (bufoff) + ldsw + _i * 8192), 16, 0, 0); } while (0)
; #define PG8_LDA(dst, b, h) do { _Pragma("unroll") for (int m = 0; m < 4; ++m) _Pragma("unroll") for (int k = 0; k < 2; ++k) dst[m][k] = *(const PG8_LAS bf16x8*)(lds + PG8_SA(b, h) + aoff + m * 2048 + k * 1024); } while (0)
; #define PG8_LDB(dst, b, h) do { _Pragma("unroll") for (int n = 0; n < 2; ++n) _Pragma("unroll") for (int k = 0; k < 2; ++k) dst[n][k] = *(const PG8_LAS bf16x8*)(lds + PG8_SB(b, h) + boff + n * 2048 + k * 1024); } while (0)
; #define PG8_MMA(ai, bj, At, Bt) do { __builtin_amdgcn_s_setprio(1); _Pragma("unroll") for (int m = 0; m < 4; ++m) _Pragma("unroll") for (int n = 0; n < 2; ++n) _Pragma("unroll") for (int k = 0; k < 2; ++k) \
;         acc[ai][bj][m][n] = __builtin_amdgcn_mfma_f32_16x16x32_bf16(Bt[n][k], At[m][k], acc[ai][bj][m][n], 0, 0, 0); __builtin_amdgcn_s_setprio(0); } while (0)
; #define PG8_WAIT_V(n) asm volatile("s_waitcnt vmcnt(" #n ")" ::: "memory")
; #define PG8_WAIT_L(n) asm volatile("s_waitcnt lgkmcnt(" #n ")" ::: "memory")
; #define PG8_BAR __builtin_amdgcn_s_barrier()
; #define PG8_SCHED __builtin_amdgcn_sched_barrier(0)
; template <class Epi, class Sched, bool ALIGN_EPI = false, bool SP2 = false>
; __device__ __forceinline__ void gemm_phase(PG8_LAS unsigned char* lds, const Gemm g, const Sched& S, const Epi& E) {
;     ...
;             PG8_LDB(B0, 1, 0); PG8_LDB(B1, 1, 1); PG8_SCHED; PG8_LDA(At, 1, 0); PG8_STAGE(PG8_SA(0, 1), a2 + hstepA, voffA);
;             PG8_WAIT_V(8); PG8_WAIT_L(0); PG8_BAR; PG8_MMA(0, 0, At, B0); PG8_MMA(0, 1, At, B1); PG8_BAR; PG8_SCHED;
;             PG8_LDA(At, 1, 1); PG8_STAGE(PG8_SB(1, 0), b3, voffB); PG8_STAGE(PG8_SB(1, 1), b3 + hstepB, voffB); PG8_STAGE(PG8_SA(1, 0), a3, voffA);
;             PG8_WAIT_V(8); PG8_WAIT_L(0); PG8_BAR; PG8_MMA(1, 0, At, B0); PG8_MMA(1, 1, At, B1); PG8_BAR; PG8_SCHED;
	s_add_i32 s57, 0, 0x18000
	s_add_i32 s58, 0, 0x1c000
	v_add_u32_e32 v140, s57, v175
	v_add_u32_e32 v179, s58, v175
	ds_read_b128 v[128:131], v140
	ds_read_b128 v[132:135], v140 offset:1024
	ds_read_b128 v[136:139], v140 offset:2048
	ds_read_b128 v[140:143], v140 offset:3072
	ds_read_b128 v[162:165], v179
	ds_read_b128 v[166:169], v179 offset:1024
	ds_read_b128 v[170:173], v179 offset:2048
	ds_read_b128 v[180:183], v179 offset:3072
	s_add_u32 s38, s38, 0x40000
	s_addc_u32 s39, s39, 0
	s_mov_b32 m0, s43
	ds_read_b128 v[186:189], v178 offset:32768
	ds_read_b128 v[190:193], v178 offset:33792
	ds_read_b128 v[194:197], v178 offset:34816
	ds_read_b128 v[198:201], v178 offset:35840
	ds_read_b128 v[202:205], v178 offset:36864
	ds_read_b128 v[206:209], v178 offset:37888
	ds_read_b128 v[210:213], v178 offset:38912
	ds_read_b128 v[214:217], v178 offset:39936
	global_load_lds_dwordx4 v144, s[38:39]
	s_mov_b32 m0, s44
	s_nop 0
	global_load_lds_dwordx4 v148, s[38:39]
	s_waitcnt vmcnt(8)
	s_waitcnt lgkmcnt(0)
	s_barrier
	s_setprio 1
	s_waitcnt lgkmcnt(0)
	v_mfma_f32_16x16x32_bf16 v[124:127], v[128:131], v[186:189], v[124:127]
	v_mfma_f32_16x16x32_bf16 v[120:123], v[136:139], v[186:189], v[120:123]
	v_mfma_f32_16x16x32_bf16 v[108:111], v[128:131], v[194:197], v[108:111]
	v_mfma_f32_16x16x32_bf16 v[104:107], v[136:139], v[194:197], v[104:107]
	v_mfma_f32_16x16x32_bf16 v[92:95], v[128:131], v[202:205], v[92:95]
	v_mfma_f32_16x16x32_bf16 v[88:91], v[136:139], v[202:205], v[88:91]
	v_mfma_f32_16x16x32_bf16 v[76:79], v[128:131], v[210:213], v[76:79]
	v_mfma_f32_16x16x32_bf16 v[72:75], v[136:139], v[210:213], v[72:75]
	v_mfma_f32_16x16x32_bf16 v[124:127], v[132:135], v[190:193], v[124:127]
	v_mfma_f32_16x16x32_bf16 v[120:123], v[140:143], v[190:193], v[120:123]
	v_mfma_f32_16x16x32_bf16 v[108:111], v[132:135], v[198:201], v[108:111]
	v_mfma_f32_16x16x32_bf16 v[104:107], v[140:143], v[198:201], v[104:107]
	v_mfma_f32_16x16x32_bf16 v[92:95], v[132:135], v[206:209], v[92:95]
	v_mfma_f32_16x16x32_bf16 v[88:91], v[140:143], v[206:209], v[88:91]
	v_mfma_f32_16x16x32_bf16 v[76:79], v[132:135], v[214:217], v[76:79]
	v_mfma_f32_16x16x32_bf16 v[72:75], v[140:143], v[214:217], v[72:75]
	v_mfma_f32_16x16x32_bf16 v[116:119], v[162:165], v[186:189], v[116:119]
	v_mfma_f32_16x16x32_bf16 v[112:115], v[170:173], v[186:189], v[112:115]
	v_mfma_f32_16x16x32_bf16 v[100:103], v[162:165], v[194:197], v[100:103]
	v_mfma_f32_16x16x32_bf16 v[96:99], v[170:173], v[194:197], v[96:99]
	v_mfma_f32_16x16x32_bf16 v[84:87], v[162:165], v[202:205], v[84:87]
	v_mfma_f32_16x16x32_bf16 v[80:83], v[170:173], v[202:205], v[80:83]
	v_mfma_f32_16x16x32_bf16 v[68:71], v[162:165], v[210:213], v[68:71]
	v_mfma_f32_16x16x32_bf16 v[64:67], v[170:173], v[210:213], v[64:67]
	v_mfma_f32_16x16x32_bf16 v[116:119], v[166:169], v[190:193], v[116:119]
	v_mfma_f32_16x16x32_bf16 v[112:115], v[180:183], v[190:193], v[112:115]
	v_mfma_f32_16x16x32_bf16 v[100:103], v[166:169], v[198:201], v[100:103]
	v_mfma_f32_16x16x32_bf16 v[96:99], v[180:183], v[198:201], v[96:99]
	v_mfma_f32_16x16x32_bf16 v[84:87], v[166:169], v[206:209], v[84:87]
	v_mfma_f32_16x16x32_bf16 v[80:83], v[180:183], v[206:209], v[80:83]
	v_mfma_f32_16x16x32_bf16 v[68:71], v[166:169], v[214:217], v[68:71]
	v_mfma_f32_16x16x32_bf16 v[64:67], v[180:183], v[214:217], v[64:67]
	s_setprio 0
	s_barrier
	s_add_i32 s38, s57, s40
	s_add_u32 s82, s36, s12
	s_addc_u32 s83, s37, s13
	s_mov_b32 m0, s38
	ds_read_b128 v[186:189], v178 offset:49152
	ds_read_b128 v[190:193], v178 offset:50176
	ds_read_b128 v[194:197], v178 offset:51200
	ds_read_b128 v[198:201], v178 offset:52224
	ds_read_b128 v[202:205], v178 offset:53248
	ds_read_b128 v[206:209], v178 offset:54272
	ds_read_b128 v[210:213], v178 offset:55296
	ds_read_b128 v[214:217], v178 offset:56320
	global_load_lds_dwordx4 v146, s[82:83]
	s_add_i32 m0, s38, 0x2000
	s_add_u32 s36, s36, 0x40080
	s_addc_u32 s37, s37, 0
	s_add_i32 s38, s58, s40
	global_load_lds_dwordx4 v150, s[82:83]
	s_mov_b32 m0, s38
	s_nop 0
	global_load_lds_dwordx4 v146, s[36:37]
	s_add_i32 m0, s38, 0x2000
	s_nop 0
	global_load_lds_dwordx4 v150, s[36:37]
	s_mov_b32 m0, s45
	s_nop 0
	global_load_lds_dwordx4 v144, s[80:81]
	s_mov_b32 m0, s46
	s_nop 0
	global_load_lds_dwordx4 v148, s[80:81]
	s_waitcnt vmcnt(8)
	s_waitcnt lgkmcnt(0)
	s_barrier
	s_setprio 1
	s_waitcnt lgkmcnt(0)
	v_mfma_f32_16x16x32_bf16 v[60:63], v[128:131], v[186:189], v[60:63]
	v_mfma_f32_16x16x32_bf16 v[56:59], v[136:139], v[186:189], v[56:59]
	v_mfma_f32_16x16x32_bf16 v[44:47], v[128:131], v[194:197], v[44:47]
	v_mfma_f32_16x16x32_bf16 v[40:43], v[136:139], v[194:197], v[40:43]
	v_mfma_f32_16x16x32_bf16 v[28:31], v[128:131], v[202:205], v[28:31]
	v_mfma_f32_16x16x32_bf16 v[24:27], v[136:139], v[202:205], v[24:27]
	v_mfma_f32_16x16x32_bf16 v[12:15], v[128:131], v[210:213], v[12:15]
	v_mfma_f32_16x16x32_bf16 v[8:11], v[136:139], v[210:213], v[8:11]
	v_mfma_f32_16x16x32_bf16 v[60:63], v[132:135], v[190:193], v[60:63]
	v_mfma_f32_16x16x32_bf16 v[56:59], v[140:143], v[190:193], v[56:59]
	v_mfma_f32_16x16x32_bf16 v[44:47], v[132:135], v[198:201], v[44:47]
	v_mfma_f32_16x16x32_bf16 v[40:43], v[140:143], v[198:201], v[40:43]
	v_mfma_f32_16x16x32_bf16 v[28:31], v[132:135], v[206:209], v[28:31]
	v_mfma_f32_16x16x32_bf16 v[24:27], v[140:143], v[206:209], v[24:27]
	v_mfma_f32_16x16x32_bf16 v[12:15], v[132:135], v[214:217], v[12:15]
	v_mfma_f32_16x16x32_bf16 v[8:11], v[140:143], v[214:217], v[8:11]
	v_mfma_f32_16x16x32_bf16 v[52:55], v[162:165], v[186:189], v[52:55]
	v_mfma_f32_16x16x32_bf16 v[48:51], v[170:173], v[186:189], v[48:51]
	v_mfma_f32_16x16x32_bf16 v[36:39], v[162:165], v[194:197], v[36:39]
	v_mfma_f32_16x16x32_bf16 v[32:35], v[170:173], v[194:197], v[32:35]
	v_mfma_f32_16x16x32_bf16 v[20:23], v[162:165], v[202:205], v[20:23]
	v_mfma_f32_16x16x32_bf16 v[16:19], v[170:173], v[202:205], v[16:19]
	v_mfma_f32_16x16x32_bf16 v[4:7], v[162:165], v[210:213], v[4:7]
	v_mfma_f32_16x16x32_bf16 v[0:3], v[170:173], v[210:213], v[0:3]
	v_mfma_f32_16x16x32_bf16 v[52:55], v[166:169], v[190:193], v[52:55]
	v_mfma_f32_16x16x32_bf16 v[48:51], v[180:183], v[190:193], v[48:51]
	v_mfma_f32_16x16x32_bf16 v[36:39], v[166:169], v[198:201], v[36:39]
	v_mfma_f32_16x16x32_bf16 v[32:35], v[180:183], v[198:201], v[32:35]
	v_mfma_f32_16x16x32_bf16 v[20:23], v[166:169], v[206:209], v[20:23]
	v_mfma_f32_16x16x32_bf16 v[16:19], v[180:183], v[206:209], v[16:19]
	v_mfma_f32_16x16x32_bf16 v[4:7], v[166:169], v[214:217], v[4:7]
	v_mfma_f32_16x16x32_bf16 v[0:3], v[180:183], v[214:217], v[0:3]
	s_setprio 0
	s_barrier
	s_add_i32 s56, s56, 2
	s_add_u32 s34, s34, 0x100
	s_addc_u32 s35, s35, 0
	s_add_u32 s54, s54, 0x100
	s_addc_u32 s55, s55, 0
	s_cmp_gt_u32 s56, 13
	s_cbranch_scc0 .LBB0_1007
	s_and_b64 vcc, exec, s[16:17]
	s_cbranch_vccz .LBB0_1010
	s_barrier
